# v78 + out-proj epilogue: the 32 in-place residual loads issued ahead with counted waits
# baseline (speedup 1.0000x reference)
; #define PG8_LAS __attribute__((address_space(3)))
; __device__ __forceinline__ unsigned cvt_pk_bf16(float lo, float hi) { unsigned r; asm volatile("v_cvt_pk_bf16_f32 %0, %1, %2" : "=v"(r) : "v"(lo), "v"(hi)); return r; }
;     __device__ __forceinline__ void operator()(const f32x4 (&acc)[2][2][4][2], const Unit& u, int wr, int wc, int fr, int fq) const {
;         const int row0 = u.pm * BM + wr * 64 + fr, col0 = u.pn * BM + wc * 32 + 4 * fq;
;         const PG8_LAS f32x2* p = sct + u.slot * 256 + wr * 64 + fr;
; #pragma unroll
;         for (int ai = 0; ai < 2; ++ai)
; #pragma unroll
;             for (int m = 0; m < 4; ++m) {
;                 const int row = row0 + ai * HALF + m * 16; const float rg = p[ai * HALF + m * 16][1];
;                 bf16_t* brow = x1b + (size_t)row * DM + col0; float sq = 0.f;
; #pragma unroll
;                 for (int bj = 0; bj < 2; ++bj)
; #pragma unroll
;                     for (int n = 0; n < 2; ++n) {
;                         const u32x2 xw = *(const u32x2*)(brow + bj * HALF + n * 16);
;                         f32x4 v = acc[ai][bj][m][n] * rg;
;                         v[0] += __builtin_bit_cast(float, xw.x << 16); v[1] += __builtin_bit_cast(float, xw.x & 0xffff0000u); v[2] += __builtin_bit_cast(float, xw.y << 16); v[3] += __builtin_bit_cast(float, xw.y & 0xffff0000u);
;                         u32x2 w; w.x = cvt_pk_bf16(v[0], v[1]); w.y = cvt_pk_bf16(v[2], v[3]); *(u32x2*)(brow + bj * HALF + n * 16) = w;
;                         sq += (v[0] * v[0] + v[1] * v[1]) + (v[2] * v[2] + v[3] * v[3]);
;                     }
;                 sq += __shfl_xor(sq, 16); sq += __shfl_xor(sq, 32);
;                 if (fq == 0) unsafeAtomicAdd(ss2 + row, sq);
;             }
;     }
.LBB0_748:
	v_lshl_add_u32 v144, s44, 8, v148
	v_ashrrev_i32_e32 v145, 31, v144
	v_lshl_or_b32 v2, s42, 8, v151
	v_lshlrev_b64 v[146:147], 12, v[144:145]
	v_ashrrev_i32_e32 v3, 31, v2
	v_lshl_add_u64 v[146:147], s[36:37], 0, v[146:147]
	v_lshl_add_u64 v[154:155], v[2:3], 1, v[146:147]
	global_load_dwordx2 v[156:157], v[154:155], off
	v_mov_b64_e32 v[242:243], 0x10000
	v_lshl_add_u64 v[228:229], v[242:243], 0, v[154:155]
	v_mov_b64_e32 v[242:243], 0x20000
	v_lshl_add_u64 v[230:231], v[242:243], 0, v[154:155]
	v_mov_b64_e32 v[242:243], 0x30000
	v_lshl_add_u64 v[232:233], v[242:243], 0, v[154:155]
	v_mov_b64_e32 v[242:243], 0x80000
	v_lshl_add_u64 v[234:235], v[242:243], 0, v[154:155]
	v_mov_b64_e32 v[242:243], 0x90000
	v_lshl_add_u64 v[236:237], v[242:243], 0, v[154:155]
	v_mov_b64_e32 v[242:243], 0xa0000
	v_lshl_add_u64 v[238:239], v[242:243], 0, v[154:155]
	v_mov_b64_e32 v[242:243], 0xb0000
	v_lshl_add_u64 v[240:241], v[242:243], 0, v[154:155]
	global_load_dwordx2 v[166:167], v[154:155], off offset:32
	global_load_dwordx2 v[168:169], v[154:155], off offset:256
	global_load_dwordx2 v[170:171], v[154:155], off offset:288
	global_load_dwordx2 v[172:173], v[228:229], off
	global_load_dwordx2 v[174:175], v[228:229], off offset:32
	global_load_dwordx2 v[176:177], v[228:229], off offset:256
	global_load_dwordx2 v[178:179], v[228:229], off offset:288
	global_load_dwordx2 v[180:181], v[230:231], off
	global_load_dwordx2 v[182:183], v[230:231], off offset:32
	global_load_dwordx2 v[184:185], v[230:231], off offset:256
	global_load_dwordx2 v[186:187], v[230:231], off offset:288
	global_load_dwordx2 v[188:189], v[232:233], off
	global_load_dwordx2 v[190:191], v[232:233], off offset:32
	global_load_dwordx2 v[192:193], v[232:233], off offset:256
	global_load_dwordx2 v[194:195], v[232:233], off offset:288
	global_load_dwordx2 v[196:197], v[234:235], off
	global_load_dwordx2 v[198:199], v[234:235], off offset:32
	global_load_dwordx2 v[200:201], v[234:235], off offset:256
	global_load_dwordx2 v[202:203], v[234:235], off offset:288
	global_load_dwordx2 v[204:205], v[236:237], off
	global_load_dwordx2 v[206:207], v[236:237], off offset:32
	global_load_dwordx2 v[208:209], v[236:237], off offset:256
	global_load_dwordx2 v[210:211], v[236:237], off offset:288
	global_load_dwordx2 v[212:213], v[238:239], off
	global_load_dwordx2 v[214:215], v[238:239], off offset:32
	global_load_dwordx2 v[216:217], v[238:239], off offset:256
	global_load_dwordx2 v[218:219], v[238:239], off offset:288
	global_load_dwordx2 v[220:221], v[240:241], off
	global_load_dwordx2 v[222:223], v[240:241], off offset:32
	global_load_dwordx2 v[224:225], v[240:241], off offset:256
	global_load_dwordx2 v[226:227], v[240:241], off offset:288
	v_add_u32_e32 v146, s0, v150
	ds_read_b64 v[158:159], v146
	v_and_b32_e32 v162, 64, v153
	v_add_u32_e32 v162, 64, v162
	s_waitcnt lgkmcnt(0)
	v_pk_mul_f32 v[130:131], v[130:131], v[158:159] op_sel:[0,1]
	v_pk_mul_f32 v[128:129], v[128:129], v[158:159] op_sel:[0,1]
	v_pk_mul_f32 v[126:127], v[126:127], v[158:159] op_sel:[0,1]
	v_pk_mul_f32 v[124:125], v[124:125], v[158:159] op_sel:[0,1]
	v_pk_mul_f32 v[122:123], v[122:123], v[158:159] op_sel:[0,1]
	v_pk_mul_f32 v[120:121], v[120:121], v[158:159] op_sel:[0,1]
	v_pk_mul_f32 v[118:119], v[118:119], v[158:159] op_sel:[0,1]
	v_pk_mul_f32 v[116:117], v[116:117], v[158:159] op_sel:[0,1]
	s_waitcnt vmcnt(31)
	v_lshlrev_b32_e32 v1, 16, v156
	v_and_b32_e32 v147, 0xffff0000, v156
	v_lshlrev_b32_e32 v156, 16, v157
	v_and_b32_e32 v157, 0xffff0000, v157
	v_add_f32_e32 v161, v128, v1
	v_add_f32_e32 v147, v129, v147
	v_add_f32_e32 v156, v130, v156
	v_add_f32_e32 v157, v131, v157
	v_cvt_pk_bf16_f32 v128, v161, v147
	v_cvt_pk_bf16_f32 v129, v156, v157
	s_nop 0
	v_mul_f32_e32 v147, v147, v147
	global_store_dwordx2 v[154:155], v[128:129], off
	v_mul_f32_e32 v157, v157, v157
	v_fmac_f32_e32 v147, v161, v161
	v_fmac_f32_e32 v157, v156, v156
	v_add_f32_e32 v147, v147, v157
	s_waitcnt vmcnt(31)
	v_lshlrev_b32_e32 v1, 16, v166
	v_and_b32_e32 v128, 0xffff0000, v166
	v_lshlrev_b32_e32 v129, 16, v167
	v_and_b32_e32 v130, 0xffff0000, v167
	v_add_f32_e32 v131, v124, v1
	v_add_f32_e32 v128, v125, v128
	v_add_f32_e32 v129, v126, v129
	v_add_f32_e32 v130, v127, v130
	v_cvt_pk_bf16_f32 v124, v131, v128
	v_cvt_pk_bf16_f32 v125, v129, v130
	s_nop 0
	v_mul_f32_e32 v128, v128, v128
	global_store_dwordx2 v[154:155], v[124:125], off offset:32
	v_mul_f32_e32 v130, v130, v130
	v_fmac_f32_e32 v128, v131, v131
	v_fmac_f32_e32 v130, v129, v129
	v_add_f32_e32 v128, v128, v130
	v_add_f32_e32 v128, v147, v128
	s_waitcnt vmcnt(31)
	v_lshlrev_b32_e32 v1, 16, v168
	v_and_b32_e32 v124, 0xffff0000, v168
	v_lshlrev_b32_e32 v125, 16, v169
	v_and_b32_e32 v126, 0xffff0000, v169
	v_add_f32_e32 v127, v120, v1
	v_add_f32_e32 v124, v121, v124
	v_add_f32_e32 v125, v122, v125
	v_add_f32_e32 v126, v123, v126
	v_cvt_pk_bf16_f32 v120, v127, v124
	v_cvt_pk_bf16_f32 v121, v125, v126
	s_nop 0
	v_mul_f32_e32 v124, v124, v124
	v_mul_f32_e32 v126, v126, v126
	v_fmac_f32_e32 v124, v127, v127
	v_fmac_f32_e32 v126, v125, v125
	v_add_f32_e32 v124, v124, v126
	v_xor_b32_e32 v1, 16, v153
	v_cmp_lt_i32_e32 vcc, v1, v162
	v_add_f32_e32 v124, v128, v124
	global_store_dwordx2 v[154:155], v[120:121], off offset:256
	v_cndmask_b32_e32 v1, v153, v1, vcc
	v_lshlrev_b32_e32 v1, 2, v1
	s_waitcnt vmcnt(31)
	v_lshlrev_b32_e32 v125, 16, v170
	v_and_b32_e32 v122, 0xffff0000, v170
	v_lshlrev_b32_e32 v126, 16, v171
	v_and_b32_e32 v123, 0xffff0000, v171
	v_add_f32_e32 v122, v117, v122
	v_add_f32_e32 v119, v119, v123
	v_add_f32_e32 v125, v116, v125
	v_add_f32_e32 v126, v118, v126
	v_mul_f32_e32 v116, v122, v122
	v_mul_f32_e32 v117, v119, v119
	v_fmac_f32_e32 v116, v125, v125
	v_fmac_f32_e32 v117, v126, v126
	v_add_f32_e32 v116, v116, v117
	v_add_f32_e32 v116, v124, v116
	ds_bpermute_b32 v117, v1, v116
	v_xor_b32_e32 v118, 32, v153
	v_cmp_lt_i32_e32 vcc, v118, v162
	v_cvt_pk_bf16_f32 v120, v125, v122
	v_cvt_pk_bf16_f32 v121, v126, v119
	s_waitcnt lgkmcnt(0)
	v_add_f32_e32 v116, v116, v117
	global_store_dwordx2 v[154:155], v[120:121], off offset:288
	v_cndmask_b32_e32 v118, v153, v118, vcc
	v_lshlrev_b32_e32 v118, 2, v118
	ds_bpermute_b32 v117, v118, v116
	s_and_saveexec_b64 s[42:43], s[2:3]
	s_cbranch_execz .LBB0_750
	v_lshl_add_u64 v[120:121], v[144:145], 2, s[38:39]
	s_waitcnt lgkmcnt(0)
	v_add_f32_e32 v116, v116, v117
	global_atomic_add_f32 v[120:121], v116, off
; __device__ __forceinline__ unsigned cvt_pk_bf16(float lo, float hi) { unsigned r; asm volatile("v_cvt_pk_bf16_f32 %0, %1, %2" : "=v"(r) : "v"(lo), "v"(hi)); return r; }
;     __device__ __forceinline__ void operator()(const f32x4 (&acc)[2][2][4][2], const Unit& u, int wr, int wc, int fr, int fq) const {
;     ...
; #pragma unroll
;         for (int ai = 0; ai < 2; ++ai)
; #pragma unroll
;             for (int m = 0; m < 4; ++m) {
;                 const int row = row0 + ai * HALF + m * 16; const float rg = p[ai * HALF + m * 16][1];
;                 bf16_t* brow = x1b + (size_t)row * DM + col0; float sq = 0.f;
; #pragma unroll
;                 for (int bj = 0; bj < 2; ++bj)
; #pragma unroll
;                     for (int n = 0; n < 2; ++n) {
;                         const u32x2 xw = *(const u32x2*)(brow + bj * HALF + n * 16);
;                         f32x4 v = acc[ai][bj][m][n] * rg;
;                         v[0] += __builtin_bit_cast(float, xw.x << 16); v[1] += __builtin_bit_cast(float, xw.x & 0xffff0000u); v[2] += __builtin_bit_cast(float, xw.y << 16); v[3] += __builtin_bit_cast(float, xw.y & 0xffff0000u);
;                         u32x2 w; w.x = cvt_pk_bf16(v[0], v[1]); w.y = cvt_pk_bf16(v[2], v[3]); *(u32x2*)(brow + bj * HALF + n * 16) = w;
;                         sq += (v[0] * v[0] + v[1] * v[1]) + (v[2] * v[2] + v[3] * v[3]);
;                     }
;                 sq += __shfl_xor(sq, 16); sq += __shfl_xor(sq, 32);
;                 if (fq == 0) unsafeAtomicAdd(ss2 + row, sq);
.LBB0_750:
	s_or_b64 exec, exec, s[42:43]
	v_or_b32_e32 v116, 16, v144
	s_waitcnt lgkmcnt(0)
	v_ashrrev_i32_e32 v117, 31, v116
	v_lshlrev_b64 v[120:121], 12, v[116:117]
	v_lshl_add_u64 v[120:121], s[36:37], 0, v[120:121]
	v_lshl_add_u64 v[120:121], v[2:3], 1, v[120:121]
	s_nop 0
	ds_read_b64 v[124:125], v146 offset:128
	s_waitcnt lgkmcnt(0)
	v_pk_mul_f32 v[114:115], v[114:115], v[124:125] op_sel:[0,1]
	v_pk_mul_f32 v[112:113], v[112:113], v[124:125] op_sel:[0,1]
	v_pk_mul_f32 v[110:111], v[110:111], v[124:125] op_sel:[0,1]
	v_pk_mul_f32 v[108:109], v[108:109], v[124:125] op_sel:[0,1]
	v_pk_mul_f32 v[106:107], v[106:107], v[124:125] op_sel:[0,1]
	v_pk_mul_f32 v[104:105], v[104:105], v[124:125] op_sel:[0,1]
	v_pk_mul_f32 v[102:103], v[102:103], v[124:125] op_sel:[0,1]
	v_pk_mul_f32 v[100:101], v[100:101], v[124:125] op_sel:[0,1]
	s_waitcnt vmcnt(31)
	v_lshlrev_b32_e32 v119, 16, v172
	v_and_b32_e32 v122, 0xffff0000, v172
	v_lshlrev_b32_e32 v126, 16, v173
	v_and_b32_e32 v123, 0xffff0000, v173
	v_add_f32_e32 v119, v112, v119
	v_add_f32_e32 v122, v113, v122
	v_add_f32_e32 v126, v114, v126
	v_add_f32_e32 v123, v115, v123
	v_cvt_pk_bf16_f32 v112, v119, v122
	v_cvt_pk_bf16_f32 v113, v126, v123
	s_nop 0
	v_mul_f32_e32 v122, v122, v122
	global_store_dwordx2 v[120:121], v[112:113], off
	v_mul_f32_e32 v123, v123, v123
	v_fmac_f32_e32 v122, v119, v119
	v_fmac_f32_e32 v123, v126, v126
	v_add_f32_e32 v119, v122, v123
	s_waitcnt vmcnt(31)
	v_lshlrev_b32_e32 v112, 16, v174
	v_and_b32_e32 v113, 0xffff0000, v174
	v_lshlrev_b32_e32 v114, 16, v175
	v_and_b32_e32 v115, 0xffff0000, v175
	v_add_f32_e32 v112, v108, v112
	v_add_f32_e32 v113, v109, v113
	v_add_f32_e32 v114, v110, v114
	v_add_f32_e32 v115, v111, v115
	v_cvt_pk_bf16_f32 v108, v112, v113
	v_cvt_pk_bf16_f32 v109, v114, v115
	s_nop 0
	v_mul_f32_e32 v113, v113, v113
	global_store_dwordx2 v[120:121], v[108:109], off offset:32
	v_mul_f32_e32 v115, v115, v115
	v_fmac_f32_e32 v113, v112, v112
	v_fmac_f32_e32 v115, v114, v114
	v_add_f32_e32 v112, v113, v115
	v_add_f32_e32 v112, v119, v112
	s_waitcnt vmcnt(31)
	v_lshlrev_b32_e32 v108, 16, v176
	v_and_b32_e32 v109, 0xffff0000, v176
	v_lshlrev_b32_e32 v110, 16, v177
	v_and_b32_e32 v111, 0xffff0000, v177
	v_add_f32_e32 v108, v104, v108
	v_add_f32_e32 v109, v105, v109
	v_add_f32_e32 v110, v106, v110
	v_add_f32_e32 v111, v107, v111
	v_cvt_pk_bf16_f32 v104, v108, v109
	v_cvt_pk_bf16_f32 v105, v110, v111
	s_nop 0
	v_mul_f32_e32 v109, v109, v109
	v_mul_f32_e32 v111, v111, v111
	v_fmac_f32_e32 v109, v108, v108
	v_fmac_f32_e32 v111, v110, v110
	v_add_f32_e32 v108, v109, v111
	v_add_f32_e32 v108, v112, v108
	global_store_dwordx2 v[120:121], v[104:105], off offset:256
	s_waitcnt vmcnt(31)
	v_lshlrev_b32_e32 v109, 16, v178
	v_and_b32_e32 v106, 0xffff0000, v178
	v_lshlrev_b32_e32 v110, 16, v179
	v_and_b32_e32 v107, 0xffff0000, v179
	v_add_f32_e32 v106, v101, v106
	v_add_f32_e32 v103, v103, v107
	v_add_f32_e32 v109, v100, v109
	v_add_f32_e32 v110, v102, v110
	v_mul_f32_e32 v100, v106, v106
	v_mul_f32_e32 v101, v103, v103
	v_fmac_f32_e32 v100, v109, v109
	v_fmac_f32_e32 v101, v110, v110
	v_add_f32_e32 v100, v100, v101
	v_add_f32_e32 v100, v108, v100
	ds_bpermute_b32 v101, v1, v100
	v_cvt_pk_bf16_f32 v102, v109, v106
	v_cvt_pk_bf16_f32 v103, v110, v103
	global_store_dwordx2 v[120:121], v[102:103], off offset:288
	s_waitcnt lgkmcnt(0)
	v_add_f32_e32 v100, v100, v101
	ds_bpermute_b32 v101, v118, v100
	s_and_saveexec_b64 s[42:43], s[2:3]
	s_cbranch_execz .LBB0_752
	v_lshl_add_u64 v[102:103], v[116:117], 2, s[38:39]
	s_waitcnt lgkmcnt(0)
	v_add_f32_e32 v100, v100, v101
	global_atomic_add_f32 v[102:103], v100, off
.LBB0_752:
	s_or_b64 exec, exec, s[42:43]
	v_or_b32_e32 v100, 32, v144
	s_waitcnt lgkmcnt(0)
	v_ashrrev_i32_e32 v101, 31, v100
	v_lshlrev_b64 v[102:103], 12, v[100:101]
	v_lshl_add_u64 v[102:103], s[36:37], 0, v[102:103]
	v_lshl_add_u64 v[102:103], v[2:3], 1, v[102:103]
	s_nop 0
	ds_read_b64 v[106:107], v146 offset:256
	s_waitcnt lgkmcnt(0)
	v_pk_mul_f32 v[98:99], v[98:99], v[106:107] op_sel:[0,1]
	v_pk_mul_f32 v[96:97], v[96:97], v[106:107] op_sel:[0,1]
	v_pk_mul_f32 v[94:95], v[94:95], v[106:107] op_sel:[0,1]
	v_pk_mul_f32 v[92:93], v[92:93], v[106:107] op_sel:[0,1]
	v_pk_mul_f32 v[90:91], v[90:91], v[106:107] op_sel:[0,1]
	v_pk_mul_f32 v[88:89], v[88:89], v[106:107] op_sel:[0,1]
	v_pk_mul_f32 v[86:87], v[86:87], v[106:107] op_sel:[0,1]
	v_pk_mul_f32 v[84:85], v[84:85], v[106:107] op_sel:[0,1]
	s_waitcnt vmcnt(31)
	v_lshlrev_b32_e32 v108, 16, v180
	v_and_b32_e32 v104, 0xffff0000, v180
	v_lshlrev_b32_e32 v109, 16, v181
	v_and_b32_e32 v105, 0xffff0000, v181
	v_add_f32_e32 v108, v96, v108
	v_add_f32_e32 v104, v97, v104
	v_add_f32_e32 v109, v98, v109
	v_add_f32_e32 v105, v99, v105
	v_cvt_pk_bf16_f32 v96, v108, v104
	v_cvt_pk_bf16_f32 v97, v109, v105
	s_nop 0
	v_mul_f32_e32 v104, v104, v104
	global_store_dwordx2 v[102:103], v[96:97], off
	v_mul_f32_e32 v105, v105, v105
	v_fmac_f32_e32 v104, v108, v108
	v_fmac_f32_e32 v105, v109, v109
	v_add_f32_e32 v104, v104, v105
	s_waitcnt vmcnt(31)
	v_lshlrev_b32_e32 v96, 16, v182
	v_and_b32_e32 v97, 0xffff0000, v182
	v_lshlrev_b32_e32 v98, 16, v183
	v_and_b32_e32 v99, 0xffff0000, v183
	v_add_f32_e32 v96, v92, v96
	v_add_f32_e32 v97, v93, v97
	v_add_f32_e32 v98, v94, v98
	v_add_f32_e32 v99, v95, v99
	v_cvt_pk_bf16_f32 v92, v96, v97
	v_cvt_pk_bf16_f32 v93, v98, v99
	s_nop 0
	v_mul_f32_e32 v97, v97, v97
	global_store_dwordx2 v[102:103], v[92:93], off offset:32
	v_mul_f32_e32 v99, v99, v99
	v_fmac_f32_e32 v97, v96, v96
	v_fmac_f32_e32 v99, v98, v98
	v_add_f32_e32 v96, v97, v99
	v_add_f32_e32 v96, v104, v96
	s_waitcnt vmcnt(31)
	v_lshlrev_b32_e32 v92, 16, v184
	v_and_b32_e32 v93, 0xffff0000, v184
	v_lshlrev_b32_e32 v94, 16, v185
	v_and_b32_e32 v95, 0xffff0000, v185
	v_add_f32_e32 v92, v88, v92
	v_add_f32_e32 v93, v89, v93
	v_add_f32_e32 v94, v90, v94
	v_add_f32_e32 v95, v91, v95
	v_cvt_pk_bf16_f32 v88, v92, v93
	v_cvt_pk_bf16_f32 v89, v94, v95
	s_nop 0
	v_mul_f32_e32 v93, v93, v93
	v_mul_f32_e32 v95, v95, v95
	v_fmac_f32_e32 v93, v92, v92
	v_fmac_f32_e32 v95, v94, v94
	v_add_f32_e32 v92, v93, v95
	v_add_f32_e32 v92, v96, v92
	global_store_dwordx2 v[102:103], v[88:89], off offset:256
	s_waitcnt vmcnt(31)
	v_lshlrev_b32_e32 v93, 16, v186
	v_and_b32_e32 v90, 0xffff0000, v186
	v_lshlrev_b32_e32 v94, 16, v187
	v_and_b32_e32 v91, 0xffff0000, v187
	v_add_f32_e32 v90, v85, v90
	v_add_f32_e32 v87, v87, v91
	v_add_f32_e32 v93, v84, v93
	v_add_f32_e32 v94, v86, v94
	v_mul_f32_e32 v84, v90, v90
	v_mul_f32_e32 v85, v87, v87
	v_fmac_f32_e32 v84, v93, v93
	v_fmac_f32_e32 v85, v94, v94
	v_add_f32_e32 v84, v84, v85
	v_add_f32_e32 v84, v92, v84
	ds_bpermute_b32 v85, v1, v84
	v_cvt_pk_bf16_f32 v86, v93, v90
	v_cvt_pk_bf16_f32 v87, v94, v87
	global_store_dwordx2 v[102:103], v[86:87], off offset:288
	s_waitcnt lgkmcnt(0)
	v_add_f32_e32 v84, v84, v85
	ds_bpermute_b32 v85, v118, v84
	s_and_saveexec_b64 s[42:43], s[2:3]
	s_cbranch_execz .LBB0_754
; __device__ __forceinline__ unsigned cvt_pk_bf16(float lo, float hi) { unsigned r; asm volatile("v_cvt_pk_bf16_f32 %0, %1, %2" : "=v"(r) : "v"(lo), "v"(hi)); return r; }
;     __device__ __forceinline__ void operator()(const f32x4 (&acc)[2][2][4][2], const Unit& u, int wr, int wc, int fr, int fq) const {
;     ...
; #pragma unroll
;         for (int ai = 0; ai < 2; ++ai)
; #pragma unroll
;             for (int m = 0; m < 4; ++m) {
;                 const int row = row0 + ai * HALF + m * 16; const float rg = p[ai * HALF + m * 16][1];
;                 bf16_t* brow = x1b + (size_t)row * DM + col0; float sq = 0.f;
; #pragma unroll
;                 for (int bj = 0; bj < 2; ++bj)
; #pragma unroll
;                     for (int n = 0; n < 2; ++n) {
;                         const u32x2 xw = *(const u32x2*)(brow + bj * HALF + n * 16);
;                         f32x4 v = acc[ai][bj][m][n] * rg;
;                         v[0] += __builtin_bit_cast(float, xw.x << 16); v[1] += __builtin_bit_cast(float, xw.x & 0xffff0000u); v[2] += __builtin_bit_cast(float, xw.y << 16); v[3] += __builtin_bit_cast(float, xw.y & 0xffff0000u);
;                         u32x2 w; w.x = cvt_pk_bf16(v[0], v[1]); w.y = cvt_pk_bf16(v[2], v[3]); *(u32x2*)(brow + bj * HALF + n * 16) = w;
;                         sq += (v[0] * v[0] + v[1] * v[1]) + (v[2] * v[2] + v[3] * v[3]);
;                     }
;                 sq += __shfl_xor(sq, 16); sq += __shfl_xor(sq, 32);
;                 if (fq == 0) unsafeAtomicAdd(ss2 + row, sq);
	v_lshl_add_u64 v[86:87], v[100:101], 2, s[38:39]
	s_waitcnt lgkmcnt(0)
	v_add_f32_e32 v84, v84, v85
	global_atomic_add_f32 v[86:87], v84, off
.LBB0_754:
	s_or_b64 exec, exec, s[42:43]
	v_or_b32_e32 v84, 48, v144
	s_waitcnt lgkmcnt(0)
	v_ashrrev_i32_e32 v85, 31, v84
	v_lshlrev_b64 v[86:87], 12, v[84:85]
	v_lshl_add_u64 v[86:87], s[36:37], 0, v[86:87]
	v_lshl_add_u64 v[86:87], v[2:3], 1, v[86:87]
	s_nop 0
	ds_read_b64 v[90:91], v146 offset:384
	s_waitcnt lgkmcnt(0)
	v_pk_mul_f32 v[82:83], v[82:83], v[90:91] op_sel:[0,1]
	v_pk_mul_f32 v[80:81], v[80:81], v[90:91] op_sel:[0,1]
	v_pk_mul_f32 v[78:79], v[78:79], v[90:91] op_sel:[0,1]
	v_pk_mul_f32 v[76:77], v[76:77], v[90:91] op_sel:[0,1]
	v_pk_mul_f32 v[74:75], v[74:75], v[90:91] op_sel:[0,1]
	v_pk_mul_f32 v[72:73], v[72:73], v[90:91] op_sel:[0,1]
	v_pk_mul_f32 v[70:71], v[70:71], v[90:91] op_sel:[0,1]
	v_pk_mul_f32 v[68:69], v[68:69], v[90:91] op_sel:[0,1]
	s_waitcnt vmcnt(31)
	v_lshlrev_b32_e32 v92, 16, v188
	v_and_b32_e32 v88, 0xffff0000, v188
	v_lshlrev_b32_e32 v93, 16, v189
	v_and_b32_e32 v89, 0xffff0000, v189
	v_add_f32_e32 v92, v80, v92
	v_add_f32_e32 v88, v81, v88
	v_add_f32_e32 v93, v82, v93
	v_add_f32_e32 v89, v83, v89
	v_cvt_pk_bf16_f32 v80, v92, v88
	v_cvt_pk_bf16_f32 v81, v93, v89
	s_nop 0
	v_mul_f32_e32 v88, v88, v88
	global_store_dwordx2 v[86:87], v[80:81], off
	v_mul_f32_e32 v89, v89, v89
	v_fmac_f32_e32 v88, v92, v92
	v_fmac_f32_e32 v89, v93, v93
	v_add_f32_e32 v88, v88, v89
	s_waitcnt vmcnt(31)
	v_lshlrev_b32_e32 v80, 16, v190
	v_and_b32_e32 v81, 0xffff0000, v190
	v_lshlrev_b32_e32 v82, 16, v191
	v_and_b32_e32 v83, 0xffff0000, v191
	v_add_f32_e32 v80, v76, v80
	v_add_f32_e32 v81, v77, v81
	v_add_f32_e32 v82, v78, v82
	v_add_f32_e32 v83, v79, v83
	v_cvt_pk_bf16_f32 v76, v80, v81
	v_cvt_pk_bf16_f32 v77, v82, v83
	s_nop 0
	v_mul_f32_e32 v81, v81, v81
	global_store_dwordx2 v[86:87], v[76:77], off offset:32
	v_mul_f32_e32 v83, v83, v83
	v_fmac_f32_e32 v81, v80, v80
	v_fmac_f32_e32 v83, v82, v82
	v_add_f32_e32 v80, v81, v83
	v_add_f32_e32 v80, v88, v80
	s_waitcnt vmcnt(31)
	v_lshlrev_b32_e32 v76, 16, v192
	v_and_b32_e32 v77, 0xffff0000, v192
	v_lshlrev_b32_e32 v78, 16, v193
	v_and_b32_e32 v79, 0xffff0000, v193
	v_add_f32_e32 v76, v72, v76
	v_add_f32_e32 v77, v73, v77
	v_add_f32_e32 v78, v74, v78
	v_add_f32_e32 v79, v75, v79
	v_cvt_pk_bf16_f32 v72, v76, v77
	v_cvt_pk_bf16_f32 v73, v78, v79
	s_nop 0
	v_mul_f32_e32 v77, v77, v77
	v_mul_f32_e32 v79, v79, v79
	v_fmac_f32_e32 v77, v76, v76
	v_fmac_f32_e32 v79, v78, v78
	v_add_f32_e32 v76, v77, v79
	v_add_f32_e32 v76, v80, v76
	global_store_dwordx2 v[86:87], v[72:73], off offset:256
	s_waitcnt vmcnt(31)
	v_lshlrev_b32_e32 v77, 16, v194
	v_and_b32_e32 v74, 0xffff0000, v194
	v_lshlrev_b32_e32 v78, 16, v195
	v_and_b32_e32 v75, 0xffff0000, v195
	v_add_f32_e32 v74, v69, v74
	v_add_f32_e32 v71, v71, v75
	v_add_f32_e32 v77, v68, v77
	v_add_f32_e32 v78, v70, v78
	v_mul_f32_e32 v68, v74, v74
	v_mul_f32_e32 v69, v71, v71
	v_fmac_f32_e32 v68, v77, v77
	v_fmac_f32_e32 v69, v78, v78
	v_add_f32_e32 v68, v68, v69
	v_add_f32_e32 v68, v76, v68
	ds_bpermute_b32 v69, v1, v68
	v_cvt_pk_bf16_f32 v70, v77, v74
	v_cvt_pk_bf16_f32 v71, v78, v71
	global_store_dwordx2 v[86:87], v[70:71], off offset:288
	s_waitcnt lgkmcnt(0)
	v_add_f32_e32 v68, v68, v69
	ds_bpermute_b32 v69, v118, v68
	s_and_saveexec_b64 s[42:43], s[2:3]
	s_cbranch_execz .LBB0_756
	v_lshl_add_u64 v[70:71], v[84:85], 2, s[38:39]
	s_waitcnt lgkmcnt(0)
	v_add_f32_e32 v68, v68, v69
	global_atomic_add_f32 v[70:71], v68, off
.LBB0_756:
	s_or_b64 exec, exec, s[42:43]
	v_add_u32_e32 v68, 0x80, v144
	s_waitcnt lgkmcnt(0)
	v_ashrrev_i32_e32 v69, 31, v68
	v_lshlrev_b64 v[70:71], 12, v[68:69]
	v_lshl_add_u64 v[70:71], s[36:37], 0, v[70:71]
	v_lshl_add_u64 v[70:71], v[2:3], 1, v[70:71]
	s_nop 0
	ds_read_b64 v[74:75], v146 offset:1024
	s_waitcnt lgkmcnt(0)
	v_pk_mul_f32 v[66:67], v[66:67], v[74:75] op_sel:[0,1]
	v_pk_mul_f32 v[64:65], v[64:65], v[74:75] op_sel:[0,1]
	v_pk_mul_f32 v[62:63], v[62:63], v[74:75] op_sel:[0,1]
	v_pk_mul_f32 v[60:61], v[60:61], v[74:75] op_sel:[0,1]
	v_pk_mul_f32 v[58:59], v[58:59], v[74:75] op_sel:[0,1]
	v_pk_mul_f32 v[56:57], v[56:57], v[74:75] op_sel:[0,1]
	v_pk_mul_f32 v[54:55], v[54:55], v[74:75] op_sel:[0,1]
	v_pk_mul_f32 v[52:53], v[52:53], v[74:75] op_sel:[0,1]
	s_waitcnt vmcnt(31)
	v_lshlrev_b32_e32 v76, 16, v196
	v_and_b32_e32 v72, 0xffff0000, v196
	v_lshlrev_b32_e32 v77, 16, v197
	v_and_b32_e32 v73, 0xffff0000, v197
	v_add_f32_e32 v76, v64, v76
	v_add_f32_e32 v72, v65, v72
	v_add_f32_e32 v77, v66, v77
	v_add_f32_e32 v73, v67, v73
	v_cvt_pk_bf16_f32 v64, v76, v72
	v_cvt_pk_bf16_f32 v65, v77, v73
	s_nop 0
	v_mul_f32_e32 v72, v72, v72
	global_store_dwordx2 v[70:71], v[64:65], off
	v_mul_f32_e32 v73, v73, v73
	v_fmac_f32_e32 v72, v76, v76
	v_fmac_f32_e32 v73, v77, v77
	v_add_f32_e32 v72, v72, v73
	s_waitcnt vmcnt(31)
	v_lshlrev_b32_e32 v64, 16, v198
	v_and_b32_e32 v65, 0xffff0000, v198
	v_lshlrev_b32_e32 v66, 16, v199
	v_and_b32_e32 v67, 0xffff0000, v199
	v_add_f32_e32 v64, v60, v64
	v_add_f32_e32 v65, v61, v65
	v_add_f32_e32 v66, v62, v66
	v_add_f32_e32 v67, v63, v67
	v_cvt_pk_bf16_f32 v60, v64, v65
	v_cvt_pk_bf16_f32 v61, v66, v67
	s_nop 0
	v_mul_f32_e32 v65, v65, v65
	global_store_dwordx2 v[70:71], v[60:61], off offset:32
	v_mul_f32_e32 v67, v67, v67
	v_fmac_f32_e32 v65, v64, v64
	v_fmac_f32_e32 v67, v66, v66
	v_add_f32_e32 v64, v65, v67
	v_add_f32_e32 v64, v72, v64
	s_waitcnt vmcnt(31)
	v_lshlrev_b32_e32 v60, 16, v200
	v_and_b32_e32 v61, 0xffff0000, v200
	v_lshlrev_b32_e32 v62, 16, v201
	v_and_b32_e32 v63, 0xffff0000, v201
	v_add_f32_e32 v60, v56, v60
	v_add_f32_e32 v61, v57, v61
	v_add_f32_e32 v62, v58, v62
	v_add_f32_e32 v63, v59, v63
	v_cvt_pk_bf16_f32 v56, v60, v61
	v_cvt_pk_bf16_f32 v57, v62, v63
	s_nop 0
	v_mul_f32_e32 v61, v61, v61
	v_mul_f32_e32 v63, v63, v63
	v_fmac_f32_e32 v61, v60, v60
	v_fmac_f32_e32 v63, v62, v62
	v_add_f32_e32 v60, v61, v63
	v_add_f32_e32 v60, v64, v60
	global_store_dwordx2 v[70:71], v[56:57], off offset:256
	s_waitcnt vmcnt(31)
	v_lshlrev_b32_e32 v61, 16, v202
	v_and_b32_e32 v58, 0xffff0000, v202
	v_lshlrev_b32_e32 v62, 16, v203
	v_and_b32_e32 v59, 0xffff0000, v203
	v_add_f32_e32 v58, v53, v58
	v_add_f32_e32 v55, v55, v59
	v_add_f32_e32 v61, v52, v61
	v_add_f32_e32 v62, v54, v62
	v_mul_f32_e32 v52, v58, v58
	v_mul_f32_e32 v53, v55, v55
	v_fmac_f32_e32 v52, v61, v61
	v_fmac_f32_e32 v53, v62, v62
	v_add_f32_e32 v52, v52, v53
	v_add_f32_e32 v52, v60, v52
	ds_bpermute_b32 v53, v1, v52
	v_cvt_pk_bf16_f32 v54, v61, v58
	v_cvt_pk_bf16_f32 v55, v62, v55
	global_store_dwordx2 v[70:71], v[54:55], off offset:288
	s_waitcnt lgkmcnt(0)
	v_add_f32_e32 v52, v52, v53
	ds_bpermute_b32 v53, v118, v52
	s_and_saveexec_b64 s[42:43], s[2:3]
	s_cbranch_execz .LBB0_758
	v_lshl_add_u64 v[54:55], v[68:69], 2, s[38:39]
	s_waitcnt lgkmcnt(0)
	v_add_f32_e32 v52, v52, v53
	global_atomic_add_f32 v[54:55], v52, off
; __device__ __forceinline__ unsigned cvt_pk_bf16(float lo, float hi) { unsigned r; asm volatile("v_cvt_pk_bf16_f32 %0, %1, %2" : "=v"(r) : "v"(lo), "v"(hi)); return r; }
;     __device__ __forceinline__ void operator()(const f32x4 (&acc)[2][2][4][2], const Unit& u, int wr, int wc, int fr, int fq) const {
;     ...
; #pragma unroll
;         for (int ai = 0; ai < 2; ++ai)
; #pragma unroll
;             for (int m = 0; m < 4; ++m) {
;                 const int row = row0 + ai * HALF + m * 16; const float rg = p[ai * HALF + m * 16][1];
;                 bf16_t* brow = x1b + (size_t)row * DM + col0; float sq = 0.f;
; #pragma unroll
;                 for (int bj = 0; bj < 2; ++bj)
; #pragma unroll
;                     for (int n = 0; n < 2; ++n) {
;                         const u32x2 xw = *(const u32x2*)(brow + bj * HALF + n * 16);
;                         f32x4 v = acc[ai][bj][m][n] * rg;
;                         v[0] += __builtin_bit_cast(float, xw.x << 16); v[1] += __builtin_bit_cast(float, xw.x & 0xffff0000u); v[2] += __builtin_bit_cast(float, xw.y << 16); v[3] += __builtin_bit_cast(float, xw.y & 0xffff0000u);
;                         u32x2 w; w.x = cvt_pk_bf16(v[0], v[1]); w.y = cvt_pk_bf16(v[2], v[3]); *(u32x2*)(brow + bj * HALF + n * 16) = w;
;                         sq += (v[0] * v[0] + v[1] * v[1]) + (v[2] * v[2] + v[3] * v[3]);
;                     }
;                 sq += __shfl_xor(sq, 16); sq += __shfl_xor(sq, 32);
;                 if (fq == 0) unsafeAtomicAdd(ss2 + row, sq);
.LBB0_758:
	s_or_b64 exec, exec, s[42:43]
	v_add_u32_e32 v52, 0x90, v144
	s_waitcnt lgkmcnt(0)
	v_ashrrev_i32_e32 v53, 31, v52
	v_lshlrev_b64 v[54:55], 12, v[52:53]
	v_lshl_add_u64 v[54:55], s[36:37], 0, v[54:55]
	v_lshl_add_u64 v[54:55], v[2:3], 1, v[54:55]
	s_nop 0
	ds_read_b64 v[58:59], v146 offset:1152
	s_waitcnt lgkmcnt(0)
	v_pk_mul_f32 v[50:51], v[50:51], v[58:59] op_sel:[0,1]
	v_pk_mul_f32 v[48:49], v[48:49], v[58:59] op_sel:[0,1]
	v_pk_mul_f32 v[46:47], v[46:47], v[58:59] op_sel:[0,1]
	v_pk_mul_f32 v[44:45], v[44:45], v[58:59] op_sel:[0,1]
	v_pk_mul_f32 v[42:43], v[42:43], v[58:59] op_sel:[0,1]
	v_pk_mul_f32 v[40:41], v[40:41], v[58:59] op_sel:[0,1]
	v_pk_mul_f32 v[38:39], v[38:39], v[58:59] op_sel:[0,1]
	v_pk_mul_f32 v[36:37], v[36:37], v[58:59] op_sel:[0,1]
	s_waitcnt vmcnt(31)
	v_lshlrev_b32_e32 v60, 16, v204
	v_and_b32_e32 v56, 0xffff0000, v204
	v_lshlrev_b32_e32 v61, 16, v205
	v_and_b32_e32 v57, 0xffff0000, v205
	v_add_f32_e32 v60, v48, v60
	v_add_f32_e32 v56, v49, v56
	v_add_f32_e32 v61, v50, v61
	v_add_f32_e32 v57, v51, v57
	v_cvt_pk_bf16_f32 v48, v60, v56
	v_cvt_pk_bf16_f32 v49, v61, v57
	s_nop 0
	v_mul_f32_e32 v56, v56, v56
	global_store_dwordx2 v[54:55], v[48:49], off
	v_mul_f32_e32 v57, v57, v57
	v_fmac_f32_e32 v56, v60, v60
	v_fmac_f32_e32 v57, v61, v61
	v_add_f32_e32 v56, v56, v57
	s_waitcnt vmcnt(31)
	v_lshlrev_b32_e32 v48, 16, v206
	v_and_b32_e32 v49, 0xffff0000, v206
	v_lshlrev_b32_e32 v50, 16, v207
	v_and_b32_e32 v51, 0xffff0000, v207
	v_add_f32_e32 v48, v44, v48
	v_add_f32_e32 v49, v45, v49
	v_add_f32_e32 v50, v46, v50
	v_add_f32_e32 v51, v47, v51
	v_cvt_pk_bf16_f32 v44, v48, v49
	v_cvt_pk_bf16_f32 v45, v50, v51
	s_nop 0
	v_mul_f32_e32 v49, v49, v49
	global_store_dwordx2 v[54:55], v[44:45], off offset:32
	v_mul_f32_e32 v51, v51, v51
	v_fmac_f32_e32 v49, v48, v48
	v_fmac_f32_e32 v51, v50, v50
	v_add_f32_e32 v48, v49, v51
	v_add_f32_e32 v48, v56, v48
	s_waitcnt vmcnt(31)
	v_lshlrev_b32_e32 v44, 16, v208
	v_and_b32_e32 v45, 0xffff0000, v208
	v_lshlrev_b32_e32 v46, 16, v209
	v_and_b32_e32 v47, 0xffff0000, v209
	v_add_f32_e32 v44, v40, v44
	v_add_f32_e32 v45, v41, v45
	v_add_f32_e32 v46, v42, v46
	v_add_f32_e32 v47, v43, v47
	v_cvt_pk_bf16_f32 v40, v44, v45
	v_cvt_pk_bf16_f32 v41, v46, v47
	s_nop 0
	v_mul_f32_e32 v45, v45, v45
	v_mul_f32_e32 v47, v47, v47
	v_fmac_f32_e32 v45, v44, v44
	v_fmac_f32_e32 v47, v46, v46
	v_add_f32_e32 v44, v45, v47
	v_add_f32_e32 v44, v48, v44
	global_store_dwordx2 v[54:55], v[40:41], off offset:256
	s_waitcnt vmcnt(31)
	v_lshlrev_b32_e32 v45, 16, v210
	v_and_b32_e32 v42, 0xffff0000, v210
	v_lshlrev_b32_e32 v46, 16, v211
	v_and_b32_e32 v43, 0xffff0000, v211
	v_add_f32_e32 v42, v37, v42
	v_add_f32_e32 v39, v39, v43
	v_add_f32_e32 v45, v36, v45
	v_add_f32_e32 v46, v38, v46
	v_mul_f32_e32 v36, v42, v42
	v_mul_f32_e32 v37, v39, v39
	v_fmac_f32_e32 v36, v45, v45
	v_fmac_f32_e32 v37, v46, v46
	v_add_f32_e32 v36, v36, v37
	v_add_f32_e32 v36, v44, v36
	ds_bpermute_b32 v37, v1, v36
	v_cvt_pk_bf16_f32 v38, v45, v42
	v_cvt_pk_bf16_f32 v39, v46, v39
	global_store_dwordx2 v[54:55], v[38:39], off offset:288
	s_waitcnt lgkmcnt(0)
	v_add_f32_e32 v36, v36, v37
	ds_bpermute_b32 v37, v118, v36
	s_and_saveexec_b64 s[42:43], s[2:3]
	s_cbranch_execz .LBB0_760
	v_lshl_add_u64 v[38:39], v[52:53], 2, s[38:39]
	s_waitcnt lgkmcnt(0)
	v_add_f32_e32 v36, v36, v37
	global_atomic_add_f32 v[38:39], v36, off
; __device__ __forceinline__ unsigned cvt_pk_bf16(float lo, float hi) { unsigned r; asm volatile("v_cvt_pk_bf16_f32 %0, %1, %2" : "=v"(r) : "v"(lo), "v"(hi)); return r; }
;     __device__ __forceinline__ void operator()(const f32x4 (&acc)[2][2][4][2], const Unit& u, int wr, int wc, int fr, int fq) const {
;     ...
; #pragma unroll
;         for (int ai = 0; ai < 2; ++ai)
; #pragma unroll
;             for (int m = 0; m < 4; ++m) {
;                 const int row = row0 + ai * HALF + m * 16; const float rg = p[ai * HALF + m * 16][1];
;                 bf16_t* brow = x1b + (size_t)row * DM + col0; float sq = 0.f;
; #pragma unroll
;                 for (int bj = 0; bj < 2; ++bj)
; #pragma unroll
;                     for (int n = 0; n < 2; ++n) {
;                         const u32x2 xw = *(const u32x2*)(brow + bj * HALF + n * 16);
;                         f32x4 v = acc[ai][bj][m][n] * rg;
;                         v[0] += __builtin_bit_cast(float, xw.x << 16); v[1] += __builtin_bit_cast(float, xw.x & 0xffff0000u); v[2] += __builtin_bit_cast(float, xw.y << 16); v[3] += __builtin_bit_cast(float, xw.y & 0xffff0000u);
;                         u32x2 w; w.x = cvt_pk_bf16(v[0], v[1]); w.y = cvt_pk_bf16(v[2], v[3]); *(u32x2*)(brow + bj * HALF + n * 16) = w;
;                         sq += (v[0] * v[0] + v[1] * v[1]) + (v[2] * v[2] + v[3] * v[3]);
;                     }
;                 sq += __shfl_xor(sq, 16); sq += __shfl_xor(sq, 32);
;                 if (fq == 0) unsafeAtomicAdd(ss2 + row, sq);
.LBB0_760:
	s_or_b64 exec, exec, s[42:43]
	v_add_u32_e32 v36, 0xa0, v144
	s_waitcnt lgkmcnt(0)
	v_ashrrev_i32_e32 v37, 31, v36
	v_lshlrev_b64 v[38:39], 12, v[36:37]
	v_lshl_add_u64 v[38:39], s[36:37], 0, v[38:39]
	v_lshl_add_u64 v[38:39], v[2:3], 1, v[38:39]
	s_nop 0
	ds_read_b64 v[42:43], v146 offset:1280
	s_waitcnt lgkmcnt(0)
	v_pk_mul_f32 v[34:35], v[34:35], v[42:43] op_sel:[0,1]
	v_pk_mul_f32 v[32:33], v[32:33], v[42:43] op_sel:[0,1]
	v_pk_mul_f32 v[30:31], v[30:31], v[42:43] op_sel:[0,1]
	v_pk_mul_f32 v[28:29], v[28:29], v[42:43] op_sel:[0,1]
	v_pk_mul_f32 v[26:27], v[26:27], v[42:43] op_sel:[0,1]
	v_pk_mul_f32 v[24:25], v[24:25], v[42:43] op_sel:[0,1]
	v_pk_mul_f32 v[22:23], v[22:23], v[42:43] op_sel:[0,1]
	v_pk_mul_f32 v[20:21], v[20:21], v[42:43] op_sel:[0,1]
	s_waitcnt vmcnt(31)
	v_lshlrev_b32_e32 v44, 16, v212
	v_and_b32_e32 v40, 0xffff0000, v212
	v_lshlrev_b32_e32 v45, 16, v213
	v_and_b32_e32 v41, 0xffff0000, v213
	v_add_f32_e32 v44, v32, v44
	v_add_f32_e32 v40, v33, v40
	v_add_f32_e32 v45, v34, v45
	v_add_f32_e32 v41, v35, v41
	v_cvt_pk_bf16_f32 v32, v44, v40
	v_cvt_pk_bf16_f32 v33, v45, v41
	s_nop 0
	v_mul_f32_e32 v40, v40, v40
	global_store_dwordx2 v[38:39], v[32:33], off
	v_mul_f32_e32 v41, v41, v41
	v_fmac_f32_e32 v40, v44, v44
	v_fmac_f32_e32 v41, v45, v45
	v_add_f32_e32 v40, v40, v41
	s_waitcnt vmcnt(31)
	v_lshlrev_b32_e32 v32, 16, v214
	v_and_b32_e32 v33, 0xffff0000, v214
	v_lshlrev_b32_e32 v34, 16, v215
	v_and_b32_e32 v35, 0xffff0000, v215
	v_add_f32_e32 v32, v28, v32
	v_add_f32_e32 v33, v29, v33
	v_add_f32_e32 v34, v30, v34
	v_add_f32_e32 v35, v31, v35
	v_cvt_pk_bf16_f32 v28, v32, v33
	v_cvt_pk_bf16_f32 v29, v34, v35
	s_nop 0
	v_mul_f32_e32 v33, v33, v33
	global_store_dwordx2 v[38:39], v[28:29], off offset:32
	v_mul_f32_e32 v35, v35, v35
	v_fmac_f32_e32 v33, v32, v32
	v_fmac_f32_e32 v35, v34, v34
	v_add_f32_e32 v32, v33, v35
	v_add_f32_e32 v32, v40, v32
	s_waitcnt vmcnt(31)
	v_lshlrev_b32_e32 v28, 16, v216
	v_and_b32_e32 v29, 0xffff0000, v216
	v_lshlrev_b32_e32 v30, 16, v217
	v_and_b32_e32 v31, 0xffff0000, v217
	v_add_f32_e32 v28, v24, v28
	v_add_f32_e32 v29, v25, v29
	v_add_f32_e32 v30, v26, v30
	v_add_f32_e32 v31, v27, v31
	v_cvt_pk_bf16_f32 v24, v28, v29
	v_cvt_pk_bf16_f32 v25, v30, v31
	s_nop 0
	v_mul_f32_e32 v29, v29, v29
	v_mul_f32_e32 v31, v31, v31
	v_fmac_f32_e32 v29, v28, v28
	v_fmac_f32_e32 v31, v30, v30
	v_add_f32_e32 v28, v29, v31
	v_add_f32_e32 v28, v32, v28
	global_store_dwordx2 v[38:39], v[24:25], off offset:256
	s_waitcnt vmcnt(31)
	v_lshlrev_b32_e32 v29, 16, v218
	v_and_b32_e32 v26, 0xffff0000, v218
	v_lshlrev_b32_e32 v30, 16, v219
	v_and_b32_e32 v27, 0xffff0000, v219
	v_add_f32_e32 v26, v21, v26
	v_add_f32_e32 v23, v23, v27
	v_add_f32_e32 v29, v20, v29
	v_add_f32_e32 v30, v22, v30
	v_mul_f32_e32 v20, v26, v26
	v_mul_f32_e32 v21, v23, v23
	v_fmac_f32_e32 v20, v29, v29
	v_fmac_f32_e32 v21, v30, v30
	v_add_f32_e32 v20, v20, v21
	v_add_f32_e32 v20, v28, v20
	ds_bpermute_b32 v21, v1, v20
	v_cvt_pk_bf16_f32 v22, v29, v26
	v_cvt_pk_bf16_f32 v23, v30, v23
	global_store_dwordx2 v[38:39], v[22:23], off offset:288
	s_waitcnt lgkmcnt(0)
	v_add_f32_e32 v20, v20, v21
	ds_bpermute_b32 v21, v118, v20
	s_and_saveexec_b64 s[42:43], s[2:3]
	s_cbranch_execz .LBB0_762
	v_lshl_add_u64 v[22:23], v[36:37], 2, s[38:39]
	s_waitcnt lgkmcnt(0)
	v_add_f32_e32 v20, v20, v21
	global_atomic_add_f32 v[22:23], v20, off
.LBB0_762:
	s_or_b64 exec, exec, s[42:43]
	v_add_u32_e32 v20, 0xb0, v144
	s_waitcnt lgkmcnt(0)
	v_ashrrev_i32_e32 v21, 31, v20
	v_lshlrev_b64 v[22:23], 12, v[20:21]
	v_lshl_add_u64 v[22:23], s[36:37], 0, v[22:23]
	v_lshl_add_u64 v[22:23], v[2:3], 1, v[22:23]
	s_nop 0
	ds_read_b64 v[24:25], v146 offset:1408
	s_waitcnt lgkmcnt(0)
	v_pk_mul_f32 v[18:19], v[18:19], v[24:25] op_sel:[0,1]
	v_pk_mul_f32 v[16:17], v[16:17], v[24:25] op_sel:[0,1]
	v_pk_mul_f32 v[14:15], v[14:15], v[24:25] op_sel:[0,1]
	v_pk_mul_f32 v[12:13], v[12:13], v[24:25] op_sel:[0,1]
	v_pk_mul_f32 v[10:11], v[10:11], v[24:25] op_sel:[0,1]
	v_pk_mul_f32 v[8:9], v[8:9], v[24:25] op_sel:[0,1]
	v_pk_mul_f32 v[6:7], v[6:7], v[24:25] op_sel:[0,1]
	v_pk_mul_f32 v[4:5], v[4:5], v[24:25] op_sel:[0,1]
	s_waitcnt vmcnt(31)
	v_lshlrev_b32_e32 v26, 16, v220
	v_and_b32_e32 v2, 0xffff0000, v220
	v_lshlrev_b32_e32 v27, 16, v221
	v_and_b32_e32 v3, 0xffff0000, v221
	v_add_f32_e32 v26, v16, v26
	v_add_f32_e32 v28, v17, v2
	v_add_f32_e32 v18, v18, v27
	v_add_f32_e32 v19, v19, v3
	v_cvt_pk_bf16_f32 v2, v26, v28
	v_cvt_pk_bf16_f32 v3, v18, v19
	s_nop 0
	s_nop 0
	global_store_dwordx2 v[22:23], v[2:3], off
	s_waitcnt vmcnt(31)
	v_lshlrev_b32_e32 v2, 16, v222
	v_and_b32_e32 v3, 0xffff0000, v222
	v_lshlrev_b32_e32 v16, 16, v223
	v_and_b32_e32 v17, 0xffff0000, v223
	v_add_f32_e32 v27, v12, v2
	v_add_f32_e32 v29, v13, v3
	v_add_f32_e32 v14, v14, v16
	v_add_f32_e32 v15, v15, v17
	v_cvt_pk_bf16_f32 v2, v27, v29
	v_cvt_pk_bf16_f32 v3, v14, v15
	s_nop 0
	v_mul_f32_e32 v15, v15, v15
	global_store_dwordx2 v[22:23], v[2:3], off offset:32
	v_fmac_f32_e32 v15, v14, v14
	s_waitcnt vmcnt(31)
	v_lshlrev_b32_e32 v2, 16, v224
	v_and_b32_e32 v3, 0xffff0000, v224
	v_lshlrev_b32_e32 v12, 16, v225
	v_and_b32_e32 v13, 0xffff0000, v225
	v_add_f32_e32 v16, v8, v2
	v_add_f32_e32 v17, v9, v3
	v_add_f32_e32 v10, v10, v12
	v_add_f32_e32 v11, v11, v13
	v_cvt_pk_bf16_f32 v8, v16, v17
	v_cvt_pk_bf16_f32 v9, v10, v11
	s_nop 0
	v_mul_f32_e32 v12, v28, v28
	v_mul_f32_e32 v13, v19, v19
	v_fmac_f32_e32 v12, v26, v26
	v_fmac_f32_e32 v13, v18, v18
	v_add_f32_e32 v12, v12, v13
	v_mul_f32_e32 v13, v29, v29
	v_fmac_f32_e32 v13, v27, v27
	v_add_f32_e32 v13, v13, v15
	v_add_f32_e32 v12, v12, v13
	v_mul_f32_e32 v13, v17, v17
	v_mul_f32_e32 v11, v11, v11
	v_fmac_f32_e32 v13, v16, v16
	v_fmac_f32_e32 v11, v10, v10
	v_add_f32_e32 v10, v13, v11
	v_add_f32_e32 v10, v12, v10
	global_store_dwordx2 v[22:23], v[8:9], off offset:256
	s_waitcnt vmcnt(31)
	v_lshlrev_b32_e32 v11, 16, v226
	v_and_b32_e32 v2, 0xffff0000, v226
	v_lshlrev_b32_e32 v12, 16, v227
	v_and_b32_e32 v3, 0xffff0000, v227
	v_add_f32_e32 v5, v5, v2
	v_add_f32_e32 v3, v7, v3
	v_add_f32_e32 v4, v4, v11
	v_add_f32_e32 v6, v6, v12
	v_mul_f32_e32 v2, v5, v5
	v_mul_f32_e32 v7, v3, v3
	v_fmac_f32_e32 v2, v4, v4
	v_fmac_f32_e32 v7, v6, v6
	v_add_f32_e32 v2, v2, v7
	v_add_f32_e32 v2, v10, v2
	ds_bpermute_b32 v1, v1, v2
	v_cvt_pk_bf16_f32 v4, v4, v5
	v_cvt_pk_bf16_f32 v5, v6, v3
	global_store_dwordx2 v[22:23], v[4:5], off offset:288
	s_waitcnt lgkmcnt(0)
	v_add_f32_e32 v1, v2, v1
	ds_bpermute_b32 v2, v118, v1
	s_and_saveexec_b64 s[42:43], s[2:3]
	s_cbranch_execz .LBB0_764
	v_lshl_add_u64 v[4:5], v[20:21], 2, s[38:39]
	s_waitcnt lgkmcnt(0)
	v_add_f32_e32 v1, v1, v2
	global_atomic_add_f32 v[4:5], v1, off
